# c13 + relu^2 GEMM epilogues: the NaN-quieting self-max before each max(0,x) removed (2 x 128 instructions), store-data wait states kept; GEMM loop heads pinned at offset 28
# speedup vs baseline: 1.0008x; 1.0008x over previous
.LBB0_682:
	v_lshl_add_u32 v152, s46, 8, v146
	v_lshl_or_b32 v144, s78, 8, v148
	v_ashrrev_i32_e32 v153, 31, v152
	v_ashrrev_i32_e32 v145, 31, v144
	v_lshlrev_b64 v[154:155], 13, v[152:153]
	v_lshl_add_u64 v[154:155], s[6:7], 0, v[154:155]
	v_lshlrev_b64 v[156:157], 1, v[144:145]
	v_max_f32_e32 v121, 0, v121
	v_max_f32_e32 v120, 0, v120
	v_lshl_add_u64 v[144:145], v[154:155], 0, v[156:157]
	v_pk_mul_f32 v[154:155], v[120:121], v[120:121]
	v_max_f32_e32 v121, 0, v127
	v_max_f32_e32 v120, 0, v126
	v_pk_mul_f32 v[126:127], v[120:121], v[120:121]
	v_max_f32_e32 v121, 0, v123
	v_max_f32_e32 v125, 0, v125
	v_max_f32_e32 v124, 0, v124
	v_max_f32_e32 v120, 0, v122
	v_pk_mul_f32 v[124:125], v[124:125], v[124:125]
	v_pk_mul_f32 v[158:159], v[120:121], v[120:121]
	v_cvt_pk_bf16_f32 v120, v124, v125
	v_cvt_pk_bf16_f32 v121, v126, v127
	v_cvt_pk_bf16_f32 v122, v154, v155
	v_cvt_pk_bf16_f32 v123, v158, v159
	v_max_f32_e32 v113, 0, v113
	v_max_f32_e32 v112, 0, v112
	global_store_dwordx4 v[144:145], v[120:123], off
	s_nop 1
	v_pk_mul_f32 v[120:121], v[112:113], v[112:113]
	v_max_f32_e32 v113, 0, v119
	v_max_f32_e32 v112, 0, v118
	v_pk_mul_f32 v[118:119], v[112:113], v[112:113]
	v_max_f32_e32 v113, 0, v115
	v_max_f32_e32 v117, 0, v117
	v_max_f32_e32 v116, 0, v116
	v_max_f32_e32 v112, 0, v114
	v_pk_mul_f32 v[116:117], v[116:117], v[116:117]
	v_pk_mul_f32 v[122:123], v[112:113], v[112:113]
	v_cvt_pk_bf16_f32 v112, v116, v117
	v_cvt_pk_bf16_f32 v113, v118, v119
	v_cvt_pk_bf16_f32 v114, v120, v121
	v_cvt_pk_bf16_f32 v115, v122, v123
	v_max_f32_e32 v105, 0, v105
	v_max_f32_e32 v104, 0, v104
	global_store_dwordx4 v[144:145], v[112:115], off offset:256
	s_nop 1
	v_pk_mul_f32 v[114:115], v[104:105], v[104:105]
	v_max_f32_e32 v105, 0, v111
	v_max_f32_e32 v104, 0, v110
	v_or_b32_e32 v112, 16, v152
	v_pk_mul_f32 v[110:111], v[104:105], v[104:105]
	v_ashrrev_i32_e32 v113, 31, v112
	v_max_f32_e32 v105, 0, v107
	v_lshlrev_b64 v[112:113], 13, v[112:113]
	v_max_f32_e32 v109, 0, v109
	v_max_f32_e32 v108, 0, v108
	v_max_f32_e32 v104, 0, v106
	v_lshl_add_u64 v[112:113], s[6:7], 0, v[112:113]
	v_pk_mul_f32 v[108:109], v[108:109], v[108:109]
	v_pk_mul_f32 v[116:117], v[104:105], v[104:105]
	v_lshl_add_u64 v[112:113], v[112:113], 0, v[156:157]
	v_cvt_pk_bf16_f32 v104, v108, v109
	v_cvt_pk_bf16_f32 v105, v110, v111
	v_cvt_pk_bf16_f32 v106, v114, v115
	v_cvt_pk_bf16_f32 v107, v116, v117
	v_max_f32_e32 v97, 0, v97
	v_max_f32_e32 v96, 0, v96
	global_store_dwordx4 v[112:113], v[104:107], off
	s_nop 1
	v_pk_mul_f32 v[104:105], v[96:97], v[96:97]
	v_max_f32_e32 v97, 0, v103
	v_max_f32_e32 v96, 0, v102
	v_pk_mul_f32 v[102:103], v[96:97], v[96:97]
	v_max_f32_e32 v97, 0, v99
	v_max_f32_e32 v101, 0, v101
	v_max_f32_e32 v100, 0, v100
	v_max_f32_e32 v96, 0, v98
	v_pk_mul_f32 v[100:101], v[100:101], v[100:101]
	v_pk_mul_f32 v[106:107], v[96:97], v[96:97]
	v_cvt_pk_bf16_f32 v96, v100, v101
	v_cvt_pk_bf16_f32 v97, v102, v103
	v_cvt_pk_bf16_f32 v98, v104, v105
	v_cvt_pk_bf16_f32 v99, v106, v107
	v_max_f32_e32 v89, 0, v89
	v_max_f32_e32 v88, 0, v88
	global_store_dwordx4 v[112:113], v[96:99], off offset:256
	s_nop 1
	v_pk_mul_f32 v[98:99], v[88:89], v[88:89]
	v_max_f32_e32 v89, 0, v95
	v_max_f32_e32 v88, 0, v94
	v_or_b32_e32 v96, 32, v152
	v_pk_mul_f32 v[94:95], v[88:89], v[88:89]
	v_ashrrev_i32_e32 v97, 31, v96
	v_max_f32_e32 v89, 0, v91
	v_lshlrev_b64 v[96:97], 13, v[96:97]
	v_max_f32_e32 v93, 0, v93
	v_max_f32_e32 v92, 0, v92
	v_max_f32_e32 v88, 0, v90
	v_lshl_add_u64 v[96:97], s[6:7], 0, v[96:97]
	v_pk_mul_f32 v[92:93], v[92:93], v[92:93]
	v_pk_mul_f32 v[100:101], v[88:89], v[88:89]
	v_lshl_add_u64 v[96:97], v[96:97], 0, v[156:157]
	v_cvt_pk_bf16_f32 v88, v92, v93
	v_cvt_pk_bf16_f32 v89, v94, v95
	v_cvt_pk_bf16_f32 v90, v98, v99
	v_cvt_pk_bf16_f32 v91, v100, v101
	v_max_f32_e32 v81, 0, v81
	v_max_f32_e32 v80, 0, v80
	global_store_dwordx4 v[96:97], v[88:91], off
	s_nop 1
	v_pk_mul_f32 v[88:89], v[80:81], v[80:81]
	v_max_f32_e32 v81, 0, v87
	v_max_f32_e32 v80, 0, v86
	v_pk_mul_f32 v[86:87], v[80:81], v[80:81]
	v_max_f32_e32 v81, 0, v83
	v_max_f32_e32 v85, 0, v85
	v_max_f32_e32 v84, 0, v84
	v_max_f32_e32 v80, 0, v82
	v_pk_mul_f32 v[84:85], v[84:85], v[84:85]
	v_pk_mul_f32 v[90:91], v[80:81], v[80:81]
	v_cvt_pk_bf16_f32 v80, v84, v85
	v_cvt_pk_bf16_f32 v81, v86, v87
	v_cvt_pk_bf16_f32 v82, v88, v89
	v_cvt_pk_bf16_f32 v83, v90, v91
	v_max_f32_e32 v73, 0, v73
	v_max_f32_e32 v72, 0, v72
	global_store_dwordx4 v[96:97], v[80:83], off offset:256
	s_nop 1
	v_pk_mul_f32 v[82:83], v[72:73], v[72:73]
	v_max_f32_e32 v73, 0, v79
	v_max_f32_e32 v72, 0, v78
	v_or_b32_e32 v80, 48, v152
	v_pk_mul_f32 v[78:79], v[72:73], v[72:73]
	v_ashrrev_i32_e32 v81, 31, v80
	v_max_f32_e32 v73, 0, v75
	v_lshlrev_b64 v[80:81], 13, v[80:81]
	v_max_f32_e32 v77, 0, v77
	v_max_f32_e32 v76, 0, v76
	v_max_f32_e32 v72, 0, v74
	v_lshl_add_u64 v[80:81], s[6:7], 0, v[80:81]
	v_pk_mul_f32 v[76:77], v[76:77], v[76:77]
	v_pk_mul_f32 v[84:85], v[72:73], v[72:73]
	v_lshl_add_u64 v[80:81], v[80:81], 0, v[156:157]
	v_cvt_pk_bf16_f32 v72, v76, v77
	v_cvt_pk_bf16_f32 v73, v78, v79
	v_cvt_pk_bf16_f32 v74, v82, v83
	v_cvt_pk_bf16_f32 v75, v84, v85
	v_max_f32_e32 v65, 0, v65
	v_max_f32_e32 v64, 0, v64
	global_store_dwordx4 v[80:81], v[72:75], off
	s_nop 1
	v_pk_mul_f32 v[72:73], v[64:65], v[64:65]
	v_max_f32_e32 v65, 0, v71
	v_max_f32_e32 v64, 0, v70
	v_pk_mul_f32 v[70:71], v[64:65], v[64:65]
	v_max_f32_e32 v65, 0, v67
	v_max_f32_e32 v69, 0, v69
	v_max_f32_e32 v68, 0, v68
	v_max_f32_e32 v64, 0, v66
	v_pk_mul_f32 v[68:69], v[68:69], v[68:69]
	v_pk_mul_f32 v[74:75], v[64:65], v[64:65]
	v_cvt_pk_bf16_f32 v64, v68, v69
	v_cvt_pk_bf16_f32 v65, v70, v71
	v_cvt_pk_bf16_f32 v66, v72, v73
	v_cvt_pk_bf16_f32 v67, v74, v75
	v_max_f32_e32 v57, 0, v57
	v_max_f32_e32 v56, 0, v56
	global_store_dwordx4 v[80:81], v[64:67], off offset:256
	s_nop 1
	v_pk_mul_f32 v[66:67], v[56:57], v[56:57]
	v_max_f32_e32 v57, 0, v63
	v_max_f32_e32 v56, 0, v62
	v_pk_mul_f32 v[62:63], v[56:57], v[56:57]
	v_max_f32_e32 v61, 0, v61
	v_max_f32_e32 v60, 0, v60
	v_max_f32_e32 v57, 0, v59
	v_pk_mul_f32 v[60:61], v[60:61], v[60:61]
	v_max_f32_e32 v56, 0, v58
	v_pk_mul_f32 v[68:69], v[56:57], v[56:57]
	v_cvt_pk_bf16_f32 v56, v60, v61
	v_add_co_u32_e32 v60, vcc, s74, v144
	v_cvt_pk_bf16_f32 v57, v62, v63
	v_cvt_pk_bf16_f32 v58, v66, v67
	v_cvt_pk_bf16_f32 v59, v68, v69
	v_addc_co_u32_e32 v61, vcc, 0, v145, vcc
	v_max_f32_e32 v49, 0, v49
	v_max_f32_e32 v48, 0, v48
	global_store_dwordx4 v[60:61], v[56:59], off
	s_nop 1
	v_pk_mul_f32 v[56:57], v[48:49], v[48:49]
	v_max_f32_e32 v49, 0, v55
	v_max_f32_e32 v48, 0, v54
	v_pk_mul_f32 v[54:55], v[48:49], v[48:49]
	v_max_f32_e32 v49, 0, v51
	v_max_f32_e32 v53, 0, v53
	v_max_f32_e32 v52, 0, v52
	v_max_f32_e32 v48, 0, v50
	v_pk_mul_f32 v[52:53], v[52:53], v[52:53]
	v_pk_mul_f32 v[58:59], v[48:49], v[48:49]
	v_lshl_add_u64 v[64:65], v[144:145], 0, s[16:17]
	v_cvt_pk_bf16_f32 v48, v52, v53
	v_cvt_pk_bf16_f32 v49, v54, v55
	v_cvt_pk_bf16_f32 v50, v56, v57
	v_cvt_pk_bf16_f32 v51, v58, v59
	v_max_f32_e32 v41, 0, v41
	v_max_f32_e32 v40, 0, v40
	global_store_dwordx4 v[64:65], v[48:51], off offset:256
	s_nop 1
	v_pk_mul_f32 v[50:51], v[40:41], v[40:41]
	v_max_f32_e32 v41, 0, v47
	v_max_f32_e32 v40, 0, v46
	v_pk_mul_f32 v[46:47], v[40:41], v[40:41]
	v_max_f32_e32 v45, 0, v45
	v_max_f32_e32 v44, 0, v44
	v_max_f32_e32 v41, 0, v43
	v_pk_mul_f32 v[44:45], v[44:45], v[44:45]
	v_max_f32_e32 v40, 0, v42
	v_pk_mul_f32 v[52:53], v[40:41], v[40:41]
	v_cvt_pk_bf16_f32 v40, v44, v45
	v_add_co_u32_e32 v44, vcc, s75, v144
	v_cvt_pk_bf16_f32 v41, v46, v47
	v_cvt_pk_bf16_f32 v42, v50, v51
	v_cvt_pk_bf16_f32 v43, v52, v53
	v_addc_co_u32_e32 v45, vcc, 0, v145, vcc
	v_max_f32_e32 v33, 0, v33
	v_max_f32_e32 v32, 0, v32
	global_store_dwordx4 v[44:45], v[40:43], off
	s_nop 1
	v_pk_mul_f32 v[40:41], v[32:33], v[32:33]
	v_max_f32_e32 v33, 0, v39
	v_max_f32_e32 v32, 0, v38
	v_pk_mul_f32 v[38:39], v[32:33], v[32:33]
	v_max_f32_e32 v33, 0, v35
	v_max_f32_e32 v37, 0, v37
	v_max_f32_e32 v36, 0, v36
	v_max_f32_e32 v32, 0, v34
	v_pk_mul_f32 v[36:37], v[36:37], v[36:37]
	v_pk_mul_f32 v[42:43], v[32:33], v[32:33]
	v_lshl_add_u64 v[48:49], v[144:145], 0, s[18:19]
	v_cvt_pk_bf16_f32 v32, v36, v37
	v_cvt_pk_bf16_f32 v33, v38, v39
	v_cvt_pk_bf16_f32 v34, v40, v41
	v_cvt_pk_bf16_f32 v35, v42, v43
	v_max_f32_e32 v25, 0, v25
	v_max_f32_e32 v24, 0, v24
	global_store_dwordx4 v[48:49], v[32:35], off offset:256
	s_nop 1
	v_pk_mul_f32 v[34:35], v[24:25], v[24:25]
	v_max_f32_e32 v25, 0, v31
	v_max_f32_e32 v24, 0, v30
	v_pk_mul_f32 v[30:31], v[24:25], v[24:25]
	v_max_f32_e32 v29, 0, v29
	v_max_f32_e32 v28, 0, v28
	v_max_f32_e32 v25, 0, v27
	v_pk_mul_f32 v[28:29], v[28:29], v[28:29]
	v_max_f32_e32 v24, 0, v26
	v_pk_mul_f32 v[36:37], v[24:25], v[24:25]
	v_cvt_pk_bf16_f32 v24, v28, v29
	v_add_co_u32_e32 v28, vcc, s76, v144
	v_cvt_pk_bf16_f32 v25, v30, v31
	v_cvt_pk_bf16_f32 v26, v34, v35
	v_cvt_pk_bf16_f32 v27, v36, v37
	v_addc_co_u32_e32 v29, vcc, 0, v145, vcc
	v_max_f32_e32 v17, 0, v17
	v_max_f32_e32 v16, 0, v16
	global_store_dwordx4 v[28:29], v[24:27], off
	s_nop 1
	v_pk_mul_f32 v[24:25], v[16:17], v[16:17]
	v_max_f32_e32 v17, 0, v23
	v_max_f32_e32 v16, 0, v22
	v_pk_mul_f32 v[22:23], v[16:17], v[16:17]
	v_max_f32_e32 v17, 0, v19
	v_max_f32_e32 v21, 0, v21
	v_max_f32_e32 v20, 0, v20
	v_max_f32_e32 v16, 0, v18
	v_pk_mul_f32 v[20:21], v[20:21], v[20:21]
	v_pk_mul_f32 v[26:27], v[16:17], v[16:17]
	v_lshl_add_u64 v[32:33], v[144:145], 0, s[34:35]
	v_cvt_pk_bf16_f32 v16, v20, v21
	v_cvt_pk_bf16_f32 v17, v22, v23
	v_cvt_pk_bf16_f32 v18, v24, v25
	v_cvt_pk_bf16_f32 v19, v26, v27
	v_max_f32_e32 v9, 0, v9
	v_max_f32_e32 v8, 0, v8
	global_store_dwordx4 v[32:33], v[16:19], off offset:256
	s_nop 1
	v_pk_mul_f32 v[18:19], v[8:9], v[8:9]
	v_max_f32_e32 v9, 0, v15
	v_max_f32_e32 v8, 0, v14
	v_pk_mul_f32 v[14:15], v[8:9], v[8:9]
	v_max_f32_e32 v13, 0, v13
	v_max_f32_e32 v12, 0, v12
	v_max_f32_e32 v9, 0, v11
	v_pk_mul_f32 v[12:13], v[12:13], v[12:13]
	v_max_f32_e32 v8, 0, v10
	v_pk_mul_f32 v[20:21], v[8:9], v[8:9]
	v_cvt_pk_bf16_f32 v8, v12, v13
	v_add_co_u32_e32 v12, vcc, s77, v144
	v_cvt_pk_bf16_f32 v9, v14, v15
	v_cvt_pk_bf16_f32 v10, v18, v19
	v_cvt_pk_bf16_f32 v11, v20, v21
	v_addc_co_u32_e32 v13, vcc, 0, v145, vcc
	v_max_f32_e32 v1, 0, v1
	v_max_f32_e32 v0, 0, v0
	global_store_dwordx4 v[12:13], v[8:11], off
	s_nop 1
	v_pk_mul_f32 v[8:9], v[0:1], v[0:1]
	v_max_f32_e32 v1, 0, v7
	v_max_f32_e32 v0, 0, v6
	v_pk_mul_f32 v[6:7], v[0:1], v[0:1]
	v_max_f32_e32 v1, 0, v3
	v_max_f32_e32 v5, 0, v5
	v_max_f32_e32 v4, 0, v4
	v_max_f32_e32 v0, 0, v2
	v_pk_mul_f32 v[4:5], v[4:5], v[4:5]
	v_pk_mul_f32 v[10:11], v[0:1], v[0:1]
	v_lshl_add_u64 v[16:17], v[144:145], 0, s[36:37]
	v_cvt_pk_bf16_f32 v0, v4, v5
	v_cvt_pk_bf16_f32 v1, v6, v7
	v_cvt_pk_bf16_f32 v2, v8, v9
	v_cvt_pk_bf16_f32 v3, v10, v11
	s_andn2_b64 vcc, exec, s[4:5]
	s_mov_b64 s[4:5], -1
	global_store_dwordx4 v[16:17], v[0:3], off offset:256
	s_cbranch_vccnz .LBB0_675
	s_andn2_b64 vcc, exec, s[8:9]
	s_cbranch_vccnz .LBB0_674
	s_barrier
	s_branch .LBB0_674

.LBB0_1306:
	v_lshl_add_u32 v152, s38, 8, v146
	v_lshl_or_b32 v144, s70, 8, v148
	v_ashrrev_i32_e32 v153, 31, v152
	v_ashrrev_i32_e32 v145, 31, v144
	v_lshlrev_b64 v[154:155], 13, v[152:153]
	v_lshl_add_u64 v[154:155], s[2:3], 0, v[154:155]
	v_lshlrev_b64 v[156:157], 1, v[144:145]
	v_max_f32_e32 v121, 0, v121
	v_max_f32_e32 v120, 0, v120
	v_lshl_add_u64 v[144:145], v[154:155], 0, v[156:157]
	v_pk_mul_f32 v[154:155], v[120:121], v[120:121]
	v_max_f32_e32 v121, 0, v127
	v_max_f32_e32 v120, 0, v126
	v_pk_mul_f32 v[126:127], v[120:121], v[120:121]
	v_max_f32_e32 v121, 0, v123
	v_max_f32_e32 v125, 0, v125
	v_max_f32_e32 v124, 0, v124
	v_max_f32_e32 v120, 0, v122
	v_pk_mul_f32 v[124:125], v[124:125], v[124:125]
	v_pk_mul_f32 v[158:159], v[120:121], v[120:121]
	v_cvt_pk_bf16_f32 v120, v124, v125
	v_cvt_pk_bf16_f32 v121, v126, v127
	v_cvt_pk_bf16_f32 v122, v154, v155
	v_cvt_pk_bf16_f32 v123, v158, v159
	v_max_f32_e32 v113, 0, v113
	v_max_f32_e32 v112, 0, v112
	global_store_dwordx4 v[144:145], v[120:123], off
	s_nop 1
	v_pk_mul_f32 v[120:121], v[112:113], v[112:113]
	v_max_f32_e32 v113, 0, v119
	v_max_f32_e32 v112, 0, v118
	v_pk_mul_f32 v[118:119], v[112:113], v[112:113]
	v_max_f32_e32 v113, 0, v115
	v_max_f32_e32 v117, 0, v117
	v_max_f32_e32 v116, 0, v116
	v_max_f32_e32 v112, 0, v114
	v_pk_mul_f32 v[116:117], v[116:117], v[116:117]
	v_pk_mul_f32 v[122:123], v[112:113], v[112:113]
	v_cvt_pk_bf16_f32 v112, v116, v117
	v_cvt_pk_bf16_f32 v113, v118, v119
	v_cvt_pk_bf16_f32 v114, v120, v121
	v_cvt_pk_bf16_f32 v115, v122, v123
	v_max_f32_e32 v105, 0, v105
	v_max_f32_e32 v104, 0, v104
	global_store_dwordx4 v[144:145], v[112:115], off offset:256
	s_nop 1
	v_pk_mul_f32 v[114:115], v[104:105], v[104:105]
	v_max_f32_e32 v105, 0, v111
	v_max_f32_e32 v104, 0, v110
	v_or_b32_e32 v112, 16, v152
	v_pk_mul_f32 v[110:111], v[104:105], v[104:105]
	v_ashrrev_i32_e32 v113, 31, v112
	v_max_f32_e32 v105, 0, v107
	v_lshlrev_b64 v[112:113], 13, v[112:113]
	v_max_f32_e32 v109, 0, v109
	v_max_f32_e32 v108, 0, v108
	v_max_f32_e32 v104, 0, v106
	v_lshl_add_u64 v[112:113], s[2:3], 0, v[112:113]
	v_pk_mul_f32 v[108:109], v[108:109], v[108:109]
	v_pk_mul_f32 v[116:117], v[104:105], v[104:105]
	v_lshl_add_u64 v[112:113], v[112:113], 0, v[156:157]
	v_cvt_pk_bf16_f32 v104, v108, v109
	v_cvt_pk_bf16_f32 v105, v110, v111
	v_cvt_pk_bf16_f32 v106, v114, v115
	v_cvt_pk_bf16_f32 v107, v116, v117
	v_max_f32_e32 v97, 0, v97
	v_max_f32_e32 v96, 0, v96
	global_store_dwordx4 v[112:113], v[104:107], off
	s_nop 1
	v_pk_mul_f32 v[104:105], v[96:97], v[96:97]
	v_max_f32_e32 v97, 0, v103
	v_max_f32_e32 v96, 0, v102
	v_pk_mul_f32 v[102:103], v[96:97], v[96:97]
	v_max_f32_e32 v97, 0, v99
	v_max_f32_e32 v101, 0, v101
	v_max_f32_e32 v100, 0, v100
	v_max_f32_e32 v96, 0, v98
	v_pk_mul_f32 v[100:101], v[100:101], v[100:101]
	v_pk_mul_f32 v[106:107], v[96:97], v[96:97]
	v_cvt_pk_bf16_f32 v96, v100, v101
	v_cvt_pk_bf16_f32 v97, v102, v103
	v_cvt_pk_bf16_f32 v98, v104, v105
	v_cvt_pk_bf16_f32 v99, v106, v107
	v_max_f32_e32 v89, 0, v89
	v_max_f32_e32 v88, 0, v88
	global_store_dwordx4 v[112:113], v[96:99], off offset:256
	s_nop 1
	v_pk_mul_f32 v[98:99], v[88:89], v[88:89]
	v_max_f32_e32 v89, 0, v95
	v_max_f32_e32 v88, 0, v94
	v_or_b32_e32 v96, 32, v152
	v_pk_mul_f32 v[94:95], v[88:89], v[88:89]
	v_ashrrev_i32_e32 v97, 31, v96
	v_max_f32_e32 v89, 0, v91
	v_lshlrev_b64 v[96:97], 13, v[96:97]
	v_max_f32_e32 v93, 0, v93
	v_max_f32_e32 v92, 0, v92
	v_max_f32_e32 v88, 0, v90
	v_lshl_add_u64 v[96:97], s[2:3], 0, v[96:97]
	v_pk_mul_f32 v[92:93], v[92:93], v[92:93]
	v_pk_mul_f32 v[100:101], v[88:89], v[88:89]
	v_lshl_add_u64 v[96:97], v[96:97], 0, v[156:157]
	v_cvt_pk_bf16_f32 v88, v92, v93
	v_cvt_pk_bf16_f32 v89, v94, v95
	v_cvt_pk_bf16_f32 v90, v98, v99
	v_cvt_pk_bf16_f32 v91, v100, v101
	v_max_f32_e32 v81, 0, v81
	v_max_f32_e32 v80, 0, v80
	global_store_dwordx4 v[96:97], v[88:91], off
	s_nop 1
	v_pk_mul_f32 v[88:89], v[80:81], v[80:81]
	v_max_f32_e32 v81, 0, v87
	v_max_f32_e32 v80, 0, v86
	v_pk_mul_f32 v[86:87], v[80:81], v[80:81]
	v_max_f32_e32 v81, 0, v83
	v_max_f32_e32 v85, 0, v85
	v_max_f32_e32 v84, 0, v84
	v_max_f32_e32 v80, 0, v82
	v_pk_mul_f32 v[84:85], v[84:85], v[84:85]
	v_pk_mul_f32 v[90:91], v[80:81], v[80:81]
	v_cvt_pk_bf16_f32 v80, v84, v85
	v_cvt_pk_bf16_f32 v81, v86, v87
	v_cvt_pk_bf16_f32 v82, v88, v89
	v_cvt_pk_bf16_f32 v83, v90, v91
	v_max_f32_e32 v73, 0, v73
	v_max_f32_e32 v72, 0, v72
	global_store_dwordx4 v[96:97], v[80:83], off offset:256
	s_nop 1
	v_pk_mul_f32 v[82:83], v[72:73], v[72:73]
	v_max_f32_e32 v73, 0, v79
	v_max_f32_e32 v72, 0, v78
	v_or_b32_e32 v80, 48, v152
	v_pk_mul_f32 v[78:79], v[72:73], v[72:73]
	v_ashrrev_i32_e32 v81, 31, v80
	v_max_f32_e32 v73, 0, v75
	v_lshlrev_b64 v[80:81], 13, v[80:81]
	v_max_f32_e32 v77, 0, v77
	v_max_f32_e32 v76, 0, v76
	v_max_f32_e32 v72, 0, v74
	v_lshl_add_u64 v[80:81], s[2:3], 0, v[80:81]
	v_pk_mul_f32 v[76:77], v[76:77], v[76:77]
	v_pk_mul_f32 v[84:85], v[72:73], v[72:73]
	v_lshl_add_u64 v[80:81], v[80:81], 0, v[156:157]
	v_cvt_pk_bf16_f32 v72, v76, v77
	v_cvt_pk_bf16_f32 v73, v78, v79
	v_cvt_pk_bf16_f32 v74, v82, v83
	v_cvt_pk_bf16_f32 v75, v84, v85
	v_max_f32_e32 v65, 0, v65
	v_max_f32_e32 v64, 0, v64
	global_store_dwordx4 v[80:81], v[72:75], off
	s_nop 1
	v_pk_mul_f32 v[72:73], v[64:65], v[64:65]
	v_max_f32_e32 v65, 0, v71
	v_max_f32_e32 v64, 0, v70
	v_pk_mul_f32 v[70:71], v[64:65], v[64:65]
	v_max_f32_e32 v65, 0, v67
	v_max_f32_e32 v69, 0, v69
	v_max_f32_e32 v68, 0, v68
	v_max_f32_e32 v64, 0, v66
	v_pk_mul_f32 v[68:69], v[68:69], v[68:69]
	v_pk_mul_f32 v[74:75], v[64:65], v[64:65]
	v_cvt_pk_bf16_f32 v64, v68, v69
	v_cvt_pk_bf16_f32 v65, v70, v71
	v_cvt_pk_bf16_f32 v66, v72, v73
	v_cvt_pk_bf16_f32 v67, v74, v75
	v_max_f32_e32 v57, 0, v57
	v_max_f32_e32 v56, 0, v56
	global_store_dwordx4 v[80:81], v[64:67], off offset:256
	s_nop 1
	v_pk_mul_f32 v[66:67], v[56:57], v[56:57]
	v_max_f32_e32 v57, 0, v63
	v_max_f32_e32 v56, 0, v62
	v_pk_mul_f32 v[62:63], v[56:57], v[56:57]
	v_max_f32_e32 v61, 0, v61
	v_max_f32_e32 v60, 0, v60
	v_max_f32_e32 v57, 0, v59
	v_pk_mul_f32 v[60:61], v[60:61], v[60:61]
	v_max_f32_e32 v56, 0, v58
	v_pk_mul_f32 v[68:69], v[56:57], v[56:57]
	v_cvt_pk_bf16_f32 v56, v60, v61
	v_add_co_u32_e32 v60, vcc, s66, v144
	v_cvt_pk_bf16_f32 v57, v62, v63
	v_cvt_pk_bf16_f32 v58, v66, v67
	v_cvt_pk_bf16_f32 v59, v68, v69
	v_addc_co_u32_e32 v61, vcc, 0, v145, vcc
	v_max_f32_e32 v49, 0, v49
	v_max_f32_e32 v48, 0, v48
	global_store_dwordx4 v[60:61], v[56:59], off
	s_nop 1
	v_pk_mul_f32 v[56:57], v[48:49], v[48:49]
	v_max_f32_e32 v49, 0, v55
	v_max_f32_e32 v48, 0, v54
	v_pk_mul_f32 v[54:55], v[48:49], v[48:49]
	v_max_f32_e32 v49, 0, v51
	v_max_f32_e32 v53, 0, v53
	v_max_f32_e32 v52, 0, v52
	v_max_f32_e32 v48, 0, v50
	v_pk_mul_f32 v[52:53], v[52:53], v[52:53]
	v_pk_mul_f32 v[58:59], v[48:49], v[48:49]
	v_lshl_add_u64 v[64:65], v[144:145], 0, s[12:13]
	v_cvt_pk_bf16_f32 v48, v52, v53
	v_cvt_pk_bf16_f32 v49, v54, v55
	v_cvt_pk_bf16_f32 v50, v56, v57
	v_cvt_pk_bf16_f32 v51, v58, v59
	v_max_f32_e32 v41, 0, v41
	v_max_f32_e32 v40, 0, v40
	global_store_dwordx4 v[64:65], v[48:51], off offset:256
	s_nop 1
	v_pk_mul_f32 v[50:51], v[40:41], v[40:41]
	v_max_f32_e32 v41, 0, v47
	v_max_f32_e32 v40, 0, v46
	v_pk_mul_f32 v[46:47], v[40:41], v[40:41]
	v_max_f32_e32 v45, 0, v45
	v_max_f32_e32 v44, 0, v44
	v_max_f32_e32 v41, 0, v43
	v_pk_mul_f32 v[44:45], v[44:45], v[44:45]
	v_max_f32_e32 v40, 0, v42
	v_pk_mul_f32 v[52:53], v[40:41], v[40:41]
	v_cvt_pk_bf16_f32 v40, v44, v45
	v_add_co_u32_e32 v44, vcc, s67, v144
	v_cvt_pk_bf16_f32 v41, v46, v47
	v_cvt_pk_bf16_f32 v42, v50, v51
	v_cvt_pk_bf16_f32 v43, v52, v53
	v_addc_co_u32_e32 v45, vcc, 0, v145, vcc
	v_max_f32_e32 v33, 0, v33
	v_max_f32_e32 v32, 0, v32
	global_store_dwordx4 v[44:45], v[40:43], off
	s_nop 1
	v_pk_mul_f32 v[40:41], v[32:33], v[32:33]
	v_max_f32_e32 v33, 0, v39
	v_max_f32_e32 v32, 0, v38
	v_pk_mul_f32 v[38:39], v[32:33], v[32:33]
	v_max_f32_e32 v33, 0, v35
	v_max_f32_e32 v37, 0, v37
	v_max_f32_e32 v36, 0, v36
	v_max_f32_e32 v32, 0, v34
	v_pk_mul_f32 v[36:37], v[36:37], v[36:37]
	v_pk_mul_f32 v[42:43], v[32:33], v[32:33]
	v_lshl_add_u64 v[48:49], v[144:145], 0, s[16:17]
	v_cvt_pk_bf16_f32 v32, v36, v37
	v_cvt_pk_bf16_f32 v33, v38, v39
	v_cvt_pk_bf16_f32 v34, v40, v41
	v_cvt_pk_bf16_f32 v35, v42, v43
	v_max_f32_e32 v25, 0, v25
	v_max_f32_e32 v24, 0, v24
	global_store_dwordx4 v[48:49], v[32:35], off offset:256
	s_nop 1
	v_pk_mul_f32 v[34:35], v[24:25], v[24:25]
	v_max_f32_e32 v25, 0, v31
	v_max_f32_e32 v24, 0, v30
	v_pk_mul_f32 v[30:31], v[24:25], v[24:25]
	v_max_f32_e32 v29, 0, v29
	v_max_f32_e32 v28, 0, v28
	v_max_f32_e32 v25, 0, v27
	v_pk_mul_f32 v[28:29], v[28:29], v[28:29]
	v_max_f32_e32 v24, 0, v26
	v_pk_mul_f32 v[36:37], v[24:25], v[24:25]
	v_cvt_pk_bf16_f32 v24, v28, v29
	v_add_co_u32_e32 v28, vcc, s68, v144
	v_cvt_pk_bf16_f32 v25, v30, v31
	v_cvt_pk_bf16_f32 v26, v34, v35
	v_cvt_pk_bf16_f32 v27, v36, v37
	v_addc_co_u32_e32 v29, vcc, 0, v145, vcc
	v_max_f32_e32 v17, 0, v17
	v_max_f32_e32 v16, 0, v16
	global_store_dwordx4 v[28:29], v[24:27], off
	s_nop 1
	v_pk_mul_f32 v[24:25], v[16:17], v[16:17]
	v_max_f32_e32 v17, 0, v23
	v_max_f32_e32 v16, 0, v22
	v_pk_mul_f32 v[22:23], v[16:17], v[16:17]
	v_max_f32_e32 v17, 0, v19
	v_max_f32_e32 v21, 0, v21
	v_max_f32_e32 v20, 0, v20
	v_max_f32_e32 v16, 0, v18
	v_pk_mul_f32 v[20:21], v[20:21], v[20:21]
	v_pk_mul_f32 v[26:27], v[16:17], v[16:17]
	v_lshl_add_u64 v[32:33], v[144:145], 0, s[18:19]
	v_cvt_pk_bf16_f32 v16, v20, v21
	v_cvt_pk_bf16_f32 v17, v22, v23
	v_cvt_pk_bf16_f32 v18, v24, v25
	v_cvt_pk_bf16_f32 v19, v26, v27
	v_max_f32_e32 v9, 0, v9
	v_max_f32_e32 v8, 0, v8
	global_store_dwordx4 v[32:33], v[16:19], off offset:256
	s_nop 1
	v_pk_mul_f32 v[18:19], v[8:9], v[8:9]
	v_max_f32_e32 v9, 0, v15
	v_max_f32_e32 v8, 0, v14
	v_pk_mul_f32 v[14:15], v[8:9], v[8:9]
	v_max_f32_e32 v13, 0, v13
	v_max_f32_e32 v12, 0, v12
	v_max_f32_e32 v9, 0, v11
	v_pk_mul_f32 v[12:13], v[12:13], v[12:13]
	v_max_f32_e32 v8, 0, v10
	v_pk_mul_f32 v[20:21], v[8:9], v[8:9]
	v_cvt_pk_bf16_f32 v8, v12, v13
	v_add_co_u32_e32 v12, vcc, s69, v144
	v_cvt_pk_bf16_f32 v9, v14, v15
	v_cvt_pk_bf16_f32 v10, v18, v19
	v_cvt_pk_bf16_f32 v11, v20, v21
	v_addc_co_u32_e32 v13, vcc, 0, v145, vcc
	v_max_f32_e32 v1, 0, v1
	v_max_f32_e32 v0, 0, v0
	global_store_dwordx4 v[12:13], v[8:11], off
	s_nop 1
	v_pk_mul_f32 v[8:9], v[0:1], v[0:1]
	v_max_f32_e32 v1, 0, v7
	v_max_f32_e32 v0, 0, v6
	v_pk_mul_f32 v[6:7], v[0:1], v[0:1]
	v_max_f32_e32 v1, 0, v3
	v_max_f32_e32 v5, 0, v5
	v_max_f32_e32 v4, 0, v4
	v_max_f32_e32 v0, 0, v2
	v_pk_mul_f32 v[4:5], v[4:5], v[4:5]
	v_pk_mul_f32 v[10:11], v[0:1], v[0:1]
	v_lshl_add_u64 v[16:17], v[144:145], 0, s[26:27]
	v_cvt_pk_bf16_f32 v0, v4, v5
	v_cvt_pk_bf16_f32 v1, v6, v7
	v_cvt_pk_bf16_f32 v2, v8, v9
	v_cvt_pk_bf16_f32 v3, v10, v11
	s_andn2_b64 vcc, exec, s[4:5]
	s_mov_b64 s[4:5], -1
	global_store_dwordx4 v[16:17], v[0:3], off offset:256
	s_cbranch_vccnz .LBB0_1299
	s_andn2_b64 vcc, exec, s[6:7]
	s_cbranch_vccnz .LBB0_1298
	s_barrier
	s_branch .LBB0_1298
